# aligned combo12 with background-conversion start delay 2x72
# baseline (speedup 1.0000x reference)
; #define LAS __attribute__((address_space(3)))
; __device__ __forceinline__ void cv_background(Frame& F, const CvPtrs& P, int s) {
;     int tv = threadIdx.x; asm volatile("" : "+v"(tv));
;     const int w = __builtin_amdgcn_readfirstlane(tv >> 6) - 1, lane = tv & 63, nbw = F.G * (NWAVES - 1);
;     LAS float* scr = (LAS float*)(F.lds + RING_OFF + (w + 1) * 16384);
;     const int sh_ = cv_bg_share(s), hi = (sh_ + 1) * CV_BG_PER < CV_BG_TOTAL ? (sh_ + 1) * CV_BG_PER : CV_BG_TOTAL;
;     for (int j = sh_ * CV_BG_PER + F.vcu * (NWAVES - 1) + w; j < hi; j += nbw) {
; __device__ __forceinline__ void xcd_barrier_cv(const XcdBarrier& b, Frame& F, const CvPtrs& P, int s, bool local) {
;     asm volatile("s_waitcnt vmcnt(0)" ::: "memory");
;     __syncthreads();
;     if (threadIdx.x < 64) { if (threadIdx.x == 0) { if (local) xcc_barrier_thread0(b); else xcd_barrier_thread0(b); } }
;     else if (cv_bg_share(s) >= 0 && cv_bg_share(s) < CV_BG_SHARES) cv_background(F, P, s);
.LBB0_769:
	s_and_b64 vcc, exec, s[0:1]
	s_cbranch_vccz .LBB0_1015
	s_sleep 72
	s_sleep 72
	v_mov_b32_e32 v4, v0
	s_mov_b64 s[6:7], -1
	v_readfirstlane_b32 s8, v4
	s_mov_b64 s[0:1], 0
	s_cmp_lt_i32 s89, 5
	s_mov_b64 s[4:5], 0
	s_cbranch_scc1 .LBB0_787
	s_cmp_gt_i32 s89, 7
	s_cbranch_scc0 .LBB0_779
	s_cmp_gt_i32 s89, 8
	s_cbranch_scc0 .LBB0_776
	s_cmp_eq_u32 s89, 9
	s_mov_b64 s[4:5], -1
	s_cbranch_scc0 .LBB0_775
	s_mov_b64 s[4:5], 0
